# prompt-scan loop: running 32-bit offsets with SGPR bases for both load stages and the S0-history stores instead of per-step 64-bit address recomputation (about 36 fewer instructions per 2 steps)
# baseline (speedup 1.0000x reference)
; __device__ __forceinline__ void seq_item(const Params& p, unsigned char* shm, int row0, int nchunks, int h, const float* S0, float* Sout) {
;     constexpr int LD = 72, SLOT = 4 * 64 * LD + 128;
;     bf16_t* Sb = (bf16_t*)shm; bf16_t* UT = Sb + 64 * LD; bf16_t* ring = UT + 64 * LD;
;     const int tid = threadIdx.x, lane = tid & 63, wid = tid >> 6, fr = lane & 15, fq = lane >> 4;
;     const int m = wid >> 1, nv0 = 2 * (wid & 1), c0 = 16 * m + 4 * fq;
;     const int crow = tid >> 3, cseg = (tid & 7) * 8;
;     f32x4 S[2];
; #pragma unroll
;     for (int q = 0; q < 2; ++q) S[q] = S0 ? *(const f32x4*)(S0 + (16 * (nv0 + q) + fr) * 64 + c0) : (f32x4){0.f, 0.f, 0.f, 0.f};
;     const int chi0 = (row0 >> 6) * 16 + h, last = nchunks - 1;
;     struct Stage { u32x4 g[4]; f32x4 gc; };
;     auto gload = [&](int ci, Stage& G) {
;         const size_t cb = (size_t)(chi0 + ci * 16) * 4096 + crow * 64 + cseg;
;         G.g[0] = *(const u32x4*)(p.W1G + cb); G.g[1] = *(const u32x4*)(p.BPG + cb); G.g[2] = *(const u32x4*)(p.U0G + cb); G.g[3] = *(const u32x4*)(p.VKG + cb);
;         G.gc = *(const f32x4*)(p.GCG + (size_t)(chi0 + ci * 16) * 64 + (tid & 15) * 4);
;     };
;     auto park = [&](int slot, const Stage& G) {
;         bf16_t* d = ring + slot * SLOT;
; #pragma unroll
;         for (int a = 0; a < 4; ++a) *(u32x4*)(d + a * 64 * LD + crow * LD + cseg) = G.g[a];
;         if (tid < 16) *(f32x4*)((float*)(d + 4 * 64 * LD) + tid * 4) = G.gc;
;     };
;     auto body = [&](int ci, int slot, int pslot, const Stage& G) {
;         const bf16_t* W1s = ring + slot * SLOT; const bf16_t* BPs = W1s + 64 * LD; const bf16_t* U0s = BPs + 64 * LD; const bf16_t* VKs = U0s + 64 * LD;
;         const float* GCs = (const float*)(VKs + 64 * LD);
;         const size_t cb = (size_t)(chi0 + ci * 16) * 4096;
; #pragma unroll
;         for (int q = 0; q < 2; ++q) *(u32x2*)(Sb + (16 * (nv0 + q) + fr) * LD + c0) = pk_bf4(S[q]);
;         LDS_BARRIER();
;         park(pslot, G);
;         *(u32x4*)(p.Z + (size_t)(row0 + ci * 64 + crow) * LDZ + ZC_S + h * 64 + cseg) = *(const u32x4*)(Sb + crow * LD + cseg);
;         const bf16x8 w10 = ldfrag(W1s, LD, 16 * m, 0, fr, fq), w11 = ldfrag(W1s, LD, 16 * m, 32, fr, fq);
; #pragma unroll
;         for (int q = 0; q < 2; ++q) {
;             const int v = 16 * (nv0 + q) + fr;
;             f32x4 acc = up_bf4(*(const u32x2*)(U0s + v * LD + c0));
.LBB0_431:
	s_andn2_b64 vcc, exec, s[2:3]
	s_cbranch_vccnz .LBB0_443
	s_lshl_b32 s2, s40, 9
	s_and_b32 s23, s2, 0xffffe000
	s_and_b32 s20, s40, 15
	s_ashr_i32 s21, s23, 2
	s_or_b32 s6, s21, s20
	s_ashr_i32 s7, s6, 31
	s_load_dwordx8 s[12:19], s[0:1], 0x108
	s_load_dwordx2 s[90:91], s[0:1], 0xb8
	s_load_dwordx2 s[92:93], s[0:1], 0x100
	s_load_dwordx2 s[94:95], s[0:1], 0x130
	s_lshl_b64 s[2:3], s[6:7], 12
	s_waitcnt vmcnt(2)
	v_lshlrev_b32_e32 v20, 6, v164
	v_mov_b32_e32 v21, 0
	v_and_b32_e32 v22, 56, v131
	v_lshl_add_u64 v[0:1], s[2:3], 0, v[20:21]
	v_or_b32_e32 v0, v0, v22
	v_lshlrev_b64 v[0:1], 1, v[0:1]
	s_waitcnt lgkmcnt(0)
	v_lshl_add_u64 v[2:3], s[12:13], 0, v[0:1]
	s_or_b32 s2, s6, 16
	global_load_dwordx4 v[24:27], v[2:3], off
	v_lshl_add_u64 v[2:3], s[14:15], 0, v[0:1]
	s_ashr_i32 s3, s2, 31
	global_load_dwordx4 v[28:31], v[2:3], off
	v_lshl_add_u64 v[2:3], s[16:17], 0, v[0:1]
	v_lshl_add_u64 v[0:1], s[18:19], 0, v[0:1]
	s_load_dwordx2 s[10:11], s[0:1], 0x130
	s_lshl_b64 s[4:5], s[2:3], 12
	global_load_dwordx4 v[36:39], v[0:1], off
	v_lshl_add_u64 v[0:1], s[4:5], 0, v[20:21]
	v_or_b32_e32 v0, v0, v22
	v_lshlrev_b64 v[0:1], 1, v[0:1]
	global_load_dwordx4 v[32:35], v[2:3], off
	v_lshl_add_u64 v[2:3], s[12:13], 0, v[0:1]
	s_lshl_b64 s[2:3], s[2:3], 8
	global_load_dwordx4 v[4:7], v[2:3], off
	v_lshl_add_u64 v[2:3], s[14:15], 0, v[0:1]
	s_waitcnt lgkmcnt(0)
	s_add_u32 s2, s10, s2
	global_load_dwordx4 v[12:15], v[2:3], off
	v_lshl_add_u64 v[2:3], s[16:17], 0, v[0:1]
	s_addc_u32 s3, s11, s3
	global_load_dwordx4 v[8:11], v[2:3], off
	v_lshl_add_u64 v[40:41], s[18:19], 0, v[0:1]
	global_load_dwordx4 v[0:3], v120, s[2:3]
	global_load_dwordx4 v[16:19], v[40:41], off
	s_load_dwordx2 s[2:3], s[0:1], 0xb0
	v_mul_u32_u24_e32 v23, 0x48, v164
	v_lshlrev_b32_e32 v51, 1, v23
	v_lshlrev_b32_e32 v48, 1, v22
	v_cmp_gt_u32_e64 s[8:9], 16, v133
	v_add3_u32 v60, 0, v51, v48
	v_lshl_add_u32 v23, v134, 2, 0
	s_waitcnt vmcnt(8)
	ds_write_b128 v60, v[24:27] offset:18432
	s_waitcnt vmcnt(7)
	ds_write_b128 v60, v[28:31] offset:27648
	s_waitcnt vmcnt(5)
	ds_write_b128 v60, v[32:35] offset:36864
	ds_write_b128 v60, v[36:39] offset:46080
	s_and_saveexec_b64 s[4:5], s[8:9]
	s_cbranch_execz .LBB0_434
	s_lshl_b64 s[24:25], s[6:7], 8
	s_add_u32 s24, s10, s24
	s_addc_u32 s25, s11, s25
	global_load_dwordx4 v[24:27], v120, s[24:25]
	s_waitcnt vmcnt(0)
	ds_write_b128 v23, v[24:27] offset:55296
.LBB0_434:
	s_or_b64 exec, exec, s[4:5]
	s_add_i32 s4, 0, 0x12100
	s_waitcnt vmcnt(4)
	ds_write_b128 v60, v[4:7] offset:55552
	s_waitcnt vmcnt(3)
	ds_write_b128 v60, v[12:15] offset:64768
	v_add3_u32 v4, s4, v51, v48
	s_add_i32 s4, 0, 0x14500
	s_waitcnt vmcnt(2)
	ds_write_b128 v4, v[8:11]
	v_add3_u32 v4, s4, v51, v48
	s_waitcnt vmcnt(0)
	ds_write_b128 v4, v[16:19]
	s_and_saveexec_b64 s[4:5], s[8:9]
	v_add_u32_e32 v4, 0x16900, v23
	ds_write_b128 v4, v[0:3]
	s_or_b64 exec, exec, s[4:5]
	s_or_b32 s4, s6, 32
	s_ashr_i32 s5, s4, 31
	s_lshl_b64 s[24:25], s[4:5], 12
	v_lshl_add_u64 v[0:1], s[24:25], 0, v[20:21]
	v_or_b32_e32 v0, v0, v22
	s_lshl_b64 s[4:5], s[4:5], 8
	v_lshlrev_b64 v[12:13], 1, v[0:1]
	s_add_u32 s4, s10, s4
	v_lshl_add_u64 v[0:1], s[12:13], 0, v[12:13]
	v_lshl_add_u64 v[4:5], s[14:15], 0, v[12:13]
	v_lshl_add_u64 v[8:9], s[16:17], 0, v[12:13]
	v_lshl_add_u64 v[12:13], s[18:19], 0, v[12:13]
	s_addc_u32 s5, s11, s5
	global_load_dwordx4 v[0:3], v[0:1], off
	v_and_b32_e32 v61, 2, v169
	global_load_dwordx4 v[4:7], v[4:5], off
	v_or_b32_e32 v52, v20, v22
	global_load_dwordx4 v[8:11], v[8:9], off
	v_lshl_or_b32 v20, v61, 4, v161
	global_load_dwordx4 v[12:15], v[12:13], off
	v_bfe_u32 v21, v133, 4, 2
	global_load_dwordx4 v[16:19], v120, s[4:5]
	v_and_b32_e32 v23, 0x70, v164
	v_mul_u32_u24_e32 v62, 0x48, v20
	v_lshl_or_b32 v50, v21, 2, v23
	v_lshl_add_u32 v20, v62, 1, 0
	v_lshlrev_b32_e32 v22, 1, v50
	v_add_u32_e32 v24, 0x900, v20
	v_add_u32_e32 v63, v20, v22
	v_add_u32_e32 v64, v24, v22
	v_or_b32_e32 v22, v23, v161
	v_mov_b32_e32 v49, 0
	v_mul_u32_u24_e32 v65, 0x90, v22
	v_lshlrev_b32_e32 v22, 3, v21
	v_lshlrev_b32_e32 v21, 4, v21
	v_add_u32_e32 v66, v20, v21
	v_add_u32_e32 v67, v24, v21
	s_or_b32 s24, s6, 48
	s_or_b32 s25, s6, 64
	s_lshl_b64 s[6:7], s[6:7], 13
	v_and_b32_e32 v20, 0x3f80, v166
	v_mov_b32_e32 v21, v49
	v_lshl_add_u64 v[56:57], s[6:7], 0, v[20:21]
	s_add_i32 s6, s21, s20
	s_add_i32 s6, s6, 16
	s_ashr_i32 s7, s6, 31
	v_and_b32_e32 v23, 7, v133
	s_lshl_b64 s[6:7], s[6:7], 13
	s_mov_b32 s5, 0
	v_mov_b32_e32 v121, v49
	s_lshl_b32 s4, s20, 6
	v_lshlrev_b32_e32 v23, 4, v23
	v_lshl_add_u64 v[58:59], s[6:7], 0, v[20:21]
	s_mov_b32 s22, 2
	v_mov_b32_e32 v53, v49
	v_lshl_add_u64 v[54:55], s[10:11], 0, v[120:121]
	v_add_u32_e32 v68, s23, v164
	v_or_b32_e32 v56, v56, v23
	v_or_b32_e32 v58, v58, v23
	s_mov_b32 s26, -2
	s_movk_i32 s27, 0x3a00
	s_lshl_b32 s4, s4, 1
	s_mov_b64 s[6:7], 0x40000
	v_lshlrev_b32_e32 v69, 1, v22
	s_mov_b32 s28, s5
	v_mov_b32_e32 v20, v49
	v_mov_b32_e32 v22, v49
	v_mov_b32_e32 v23, v49
	v_mov_b32_e32 v24, v49
	v_mov_b32_e32 v25, v49
	v_mov_b32_e32 v26, v49
	v_mov_b32_e32 v27, v49
	s_lshl_b32 s96, s24, 13
	v_lshl_add_u32 v200, v52, 1, s96
	s_lshl_b32 s96, s24, 8
	v_add_u32_e32 v201, s96, v120
	s_lshl_b32 s96, s25, 13
	v_lshl_add_u32 v202, v52, 1, s96
	s_lshl_b32 s96, s25, 8
	v_add_u32_e32 v203, s96, v120
	v_mul_lo_u32 v204, v68, s27
	v_add3_u32 v204, v204, s4, v48
	v_add_u32_e32 v204, 0x1000, v204
	s_branch .LBB0_438
; __device__ __forceinline__ void seq_item(const Params& p, unsigned char* shm, int row0, int nchunks, int h, const float* S0, float* Sout) {
;     ...
;     auto body = [&](int ci, int slot, int pslot, const Stage& G) {
;         const bf16_t* W1s = ring + slot * SLOT; const bf16_t* BPs = W1s + 64 * LD; const bf16_t* U0s = BPs + 64 * LD; const bf16_t* VKs = U0s + 64 * LD;
;         const float* GCs = (const float*)(VKs + 64 * LD);
;         const size_t cb = (size_t)(chi0 + ci * 16) * 4096;
; #pragma unroll
;         for (int q = 0; q < 2; ++q) *(u32x2*)(Sb + (16 * (nv0 + q) + fr) * LD + c0) = pk_bf4(S[q]);
;         LDS_BARRIER();
;         park(pslot, G);
;         *(u32x4*)(p.Z + (size_t)(row0 + ci * 64 + crow) * LDZ + ZC_S + h * 64 + cseg) = *(const u32x4*)(Sb + crow * LD + cseg);
;         const bf16x8 w10 = ldfrag(W1s, LD, 16 * m, 0, fr, fq), w11 = ldfrag(W1s, LD, 16 * m, 32, fr, fq);
; #pragma unroll
;         for (int q = 0; q < 2; ++q) {
;             const int v = 16 * (nv0 + q) + fr;
;             f32x4 acc = up_bf4(*(const u32x2*)(U0s + v * LD + c0));
;             acc = MFMA16(w10, ldfrag(Sb, LD, 16 * (nv0 + q), 0, fr, fq), acc);
;             acc = MFMA16(w11, ldfrag(Sb, LD, 16 * (nv0 + q), 32, fr, fq), acc);
;             *(u32x2*)(UT + v * LD + c0) = pk_bf4(acc);
;         }
;         LDS_BARRIER();
;         *(u32x4*)(p.UTG + cb + crow * 64 + cseg) = *(const u32x4*)(UT + crow * LD + cseg);
;         const bf16x8 bp0 = ldfrag(BPs, LD, 16 * m, 0, fr, fq), bp1 = ldfrag(BPs, LD, 16 * m, 32, fr, fq);
;         const f32x4 gc = *(const f32x4*)(GCs + c0);
; #pragma unroll
;         for (int q = 0; q < 2; ++q) {
;             const int v = 16 * (nv0 + q) + fr;
;             f32x4 acc = S[q] * gc + up_bf4(*(const u32x2*)(VKs + v * LD + c0));
;             acc = MFMA16(bp0, ldfrag(UT, LD, 16 * (nv0 + q), 0, fr, fq), acc);
;             acc = MFMA16(bp1, ldfrag(UT, LD, 16 * (nv0 + q), 32, fr, fq), acc);
;             S[q] = acc;
;         }
;     };
;     Stage A, B;
;     gload(0, A); gload(min(1, last), B);
;     park(0, A); park(1, B);
;     gload(min(2, last), A);
;     int scur = 0, spark = 2;
;     for (int ci = 0; ci < nchunks; ci += 2) {
;         gload(min(ci + 3, last), B);
;         body(ci, scur, spark, A);
;         scur = scur == 2 ? 0 : scur + 1; spark = spark == 2 ? 0 : spark + 1;
;         if (ci + 1 >= nchunks) break;
.LBB0_437:
	s_or_b64 exec, exec, s[22:23]
	s_add_i32 s22, s28, 1
	s_cmp_lg_u32 s28, 2
	s_cselect_b32 s22, s22, 0
	s_mul_i32 s23, s22, 0x9100
	s_add_i32 s23, s23, 0
	v_add3_u32 v80, s23, v65, v69
	v_add3_u32 v81, s23, v70, v71
	ds_read_b64 v[38:39], v81 offset:36864
	s_waitcnt vmcnt(7)
	ds_read_b128 v[28:31], v80 offset:18496
	ds_read_b128 v[32:35], v80 offset:18432
	ds_read_b128 v[40:43], v60
	ds_read_b128 v[44:47], v66
	ds_read_b128 v[70:73], v66 offset:64
	ds_read_b128 v[74:77], v67 offset:64
	s_waitcnt lgkmcnt(6)
	v_lshlrev_b32_e32 v36, 16, v38
	v_and_b32_e32 v37, 0xffff0000, v38
	v_lshlrev_b32_e32 v38, 16, v39
	v_and_b32_e32 v39, 0xffff0000, v39
	s_nop 0
	s_waitcnt lgkmcnt(2)
	v_mfma_f32_16x16x32_bf16 v[36:39], v[32:35], v[44:47], v[36:39]
	ds_read_b128 v[44:47], v67
	s_waitcnt lgkmcnt(2)
	v_mfma_f32_16x16x32_bf16 v[36:39], v[28:31], v[70:73], v[36:39]
	v_lshl_add_u64 v[56:57], v[56:57], 0, s[6:7]
	s_nop 6
	v_cvt_pk_bf16_f32 v36, v36, v37
	v_cvt_pk_bf16_f32 v37, v38, v39
	ds_write_b64 v63, v[36:37] offset:9216
	ds_read_b64 v[38:39], v81 offset:39168
	s_waitcnt lgkmcnt(0)
	v_lshlrev_b32_e32 v36, 16, v38
	v_and_b32_e32 v37, 0xffff0000, v38
	v_lshlrev_b32_e32 v38, 16, v39
	v_and_b32_e32 v39, 0xffff0000, v39
	s_nop 1
	v_mfma_f32_16x16x32_bf16 v[32:35], v[32:35], v[44:47], v[36:39]
	global_store_dwordx4 v204, v[40:43], s[90:91] offset:2048
	v_add_u32_e32 v204, 0xe8000, v204
	v_mfma_f32_16x16x32_bf16 v[28:31], v[28:31], v[74:77], v[32:35]
	s_nop 0
	v_lshl_add_u32 v36, v50, 2, s23
	s_nop 5
	v_cvt_pk_bf16_f32 v28, v28, v29
	v_cvt_pk_bf16_f32 v29, v30, v31
	ds_write_b64 v64, v[28:29] offset:9216
	s_waitcnt lgkmcnt(0)
	s_barrier
	ds_read_b64 v[40:41], v81 offset:46080
	ds_read_b128 v[28:31], v80 offset:27712
	ds_read_b128 v[32:35], v80 offset:27648
	ds_read_b128 v[36:39], v36 offset:55296
	s_waitcnt lgkmcnt(3)
	v_lshlrev_b32_e32 v44, 16, v40
	v_and_b32_e32 v45, 0xffff0000, v40
	v_lshlrev_b32_e32 v46, 16, v41
	v_and_b32_e32 v47, 0xffff0000, v41
	ds_read_b128 v[40:43], v66 offset:9216
	ds_read_b64 v[74:75], v81 offset:48384
	s_waitcnt lgkmcnt(2)
	v_pk_fma_f32 v[26:27], v[26:27], v[38:39], v[46:47]
	v_pk_fma_f32 v[24:25], v[24:25], v[36:37], v[44:45]
	ds_read_b128 v[44:47], v67 offset:9280
	s_waitcnt lgkmcnt(2)
	v_mfma_f32_16x16x32_bf16 v[24:27], v[32:35], v[40:43], v[24:27]
	ds_read_b128 v[40:43], v66 offset:9280
	ds_read_b128 v[70:73], v67 offset:9216
	s_waitcnt lgkmcnt(1)
	v_mfma_f32_16x16x32_bf16 v[24:27], v[28:31], v[40:43], v[24:27]
	v_lshlrev_b32_e32 v40, 16, v74
	v_and_b32_e32 v41, 0xffff0000, v74
	v_lshlrev_b32_e32 v42, 16, v75
	v_and_b32_e32 v43, 0xffff0000, v75
	v_pk_fma_f32 v[22:23], v[22:23], v[38:39], v[42:43]
	v_pk_fma_f32 v[20:21], v[20:21], v[36:37], v[40:41]
	v_lshl_add_u64 v[36:37], s[10:11], 0, v[58:59]
	s_add_i32 s10, s22, 1
	s_waitcnt lgkmcnt(0)
	v_mfma_f32_16x16x32_bf16 v[20:23], v[32:35], v[70:73], v[20:23]
	ds_read_b128 v[32:35], v60 offset:9216
	s_cmp_lg_u32 s22, 2
	s_cselect_b32 s28, s10, 0
	v_mfma_f32_16x16x32_bf16 v[20:23], v[28:31], v[44:47], v[20:23]
	s_add_i32 s10, s29, 1
	s_cmp_lg_u32 s29, 2
	s_cselect_b32 s22, s10, 0
	s_cmpk_lt_u32 s26, 0x7e
	v_lshl_add_u64 v[58:59], v[58:59], 0, s[6:7]
	s_waitcnt lgkmcnt(0)
	global_store_dwordx4 v[36:37], v[32:35], off
	s_cbranch_scc0 .LBB0_442
.LBB0_438:
	s_add_i32 s26, s26, 2
	global_load_dwordx4 v[32:35], v200, s[12:13]
	global_load_dwordx4 v[36:39], v200, s[14:15]
	global_load_dwordx4 v[44:47], v200, s[18:19]
	global_load_dwordx4 v[40:43], v200, s[16:17]
	v_cvt_pk_bf16_f32 v70, v24, v25
	global_load_dwordx4 v[28:31], v201, s[94:95]
	v_cvt_pk_bf16_f32 v71, v26, v27
	v_add_u32_e32 v200, 0x40000, v200
	v_add_u32_e32 v201, 0x2000, v201
	ds_write_b64 v63, v[70:71]
	v_cvt_pk_bf16_f32 v70, v20, v21
	v_cvt_pk_bf16_f32 v71, v22, v23
	ds_write_b64 v64, v[70:71]
	s_waitcnt lgkmcnt(0)
	s_barrier
	s_mul_i32 s10, s22, 0x9100
	s_add_i32 s20, s10, 0
	v_add3_u32 v70, s20, v51, v48
	s_waitcnt vmcnt(9)
	ds_write_b128 v70, v[0:3] offset:18432
	s_waitcnt vmcnt(8)
	ds_write_b128 v70, v[4:7] offset:27648
	s_waitcnt vmcnt(7)
	ds_write_b128 v70, v[8:11] offset:36864
	s_waitcnt vmcnt(6)
	ds_write_b128 v70, v[12:15] offset:46080
	s_and_saveexec_b64 s[10:11], s[8:9]
	s_cbranch_execz .LBB0_440
	v_lshl_add_u32 v0, v134, 2, s20
	s_waitcnt vmcnt(5)
	ds_write_b128 v0, v[16:19] offset:55296
; __device__ __forceinline__ void seq_item(const Params& p, unsigned char* shm, int row0, int nchunks, int h, const float* S0, float* Sout) {
;     ...
;     auto body = [&](int ci, int slot, int pslot, const Stage& G) {
;         const bf16_t* W1s = ring + slot * SLOT; const bf16_t* BPs = W1s + 64 * LD; const bf16_t* U0s = BPs + 64 * LD; const bf16_t* VKs = U0s + 64 * LD;
;         const float* GCs = (const float*)(VKs + 64 * LD);
;         const size_t cb = (size_t)(chi0 + ci * 16) * 4096;
; #pragma unroll
;         for (int q = 0; q < 2; ++q) *(u32x2*)(Sb + (16 * (nv0 + q) + fr) * LD + c0) = pk_bf4(S[q]);
;         LDS_BARRIER();
;         park(pslot, G);
;         *(u32x4*)(p.Z + (size_t)(row0 + ci * 64 + crow) * LDZ + ZC_S + h * 64 + cseg) = *(const u32x4*)(Sb + crow * LD + cseg);
;         const bf16x8 w10 = ldfrag(W1s, LD, 16 * m, 0, fr, fq), w11 = ldfrag(W1s, LD, 16 * m, 32, fr, fq);
; #pragma unroll
;         for (int q = 0; q < 2; ++q) {
;             const int v = 16 * (nv0 + q) + fr;
;             f32x4 acc = up_bf4(*(const u32x2*)(U0s + v * LD + c0));
;             acc = MFMA16(w10, ldfrag(Sb, LD, 16 * (nv0 + q), 0, fr, fq), acc);
;             acc = MFMA16(w11, ldfrag(Sb, LD, 16 * (nv0 + q), 32, fr, fq), acc);
;             *(u32x2*)(UT + v * LD + c0) = pk_bf4(acc);
;         }
;         LDS_BARRIER();
;         *(u32x4*)(p.UTG + cb + crow * 64 + cseg) = *(const u32x4*)(UT + crow * LD + cseg);
;         const bf16x8 bp0 = ldfrag(BPs, LD, 16 * m, 0, fr, fq), bp1 = ldfrag(BPs, LD, 16 * m, 32, fr, fq);
;         const f32x4 gc = *(const f32x4*)(GCs + c0);
; #pragma unroll
;         for (int q = 0; q < 2; ++q) {
;             const int v = 16 * (nv0 + q) + fr;
;             f32x4 acc = S[q] * gc + up_bf4(*(const u32x2*)(VKs + v * LD + c0));
;             acc = MFMA16(bp0, ldfrag(UT, LD, 16 * (nv0 + q), 0, fr, fq), acc);
;             acc = MFMA16(bp1, ldfrag(UT, LD, 16 * (nv0 + q), 32, fr, fq), acc);
;             S[q] = acc;
;         }
;     };
;     Stage A, B;
;     gload(0, A); gload(min(1, last), B);
;     park(0, A); park(1, B);
;     gload(min(2, last), A);
;     int scur = 0, spark = 2;
;     for (int ci = 0; ci < nchunks; ci += 2) {
;         gload(min(ci + 3, last), B);
;         body(ci, scur, spark, A);
;         scur = scur == 2 ? 0 : scur + 1; spark = spark == 2 ? 0 : spark + 1;
;         if (ci + 1 >= nchunks) break;
.LBB0_440:
	s_or_b64 exec, exec, s[10:11]
	s_mul_i32 s10, s28, 0x9100
	s_add_i32 s34, s10, 0
	v_lshlrev_b32_e32 v70, 1, v62
	v_lshlrev_b32_e32 v71, 1, v50
	v_add3_u32 v90, s34, v70, v71
	ds_read_b64 v[10:11], v90 offset:36864
	v_add3_u32 v80, s34, v65, v69
	ds_read_b128 v[0:3], v80 offset:18432
	ds_read_b128 v[4:7], v80 offset:18496
	ds_read_b128 v[12:15], v60
	s_waitcnt vmcnt(5)
	ds_read_b128 v[16:19], v66
	s_waitcnt lgkmcnt(0)
	v_lshlrev_b32_e32 v8, 16, v10
	v_and_b32_e32 v9, 0xffff0000, v10
	v_lshlrev_b32_e32 v10, 16, v11
	v_and_b32_e32 v11, 0xffff0000, v11
	ds_read_b128 v[72:75], v66 offset:64
	s_nop 0
	v_mfma_f32_16x16x32_bf16 v[8:11], v[0:3], v[16:19], v[8:11]
	ds_read_b128 v[16:19], v67
	s_waitcnt lgkmcnt(1)
	v_mfma_f32_16x16x32_bf16 v[8:11], v[4:7], v[72:75], v[8:11]
	s_add_i32 s23, s22, 1
	s_cmp_lg_u32 s22, 2
	s_cselect_b32 s29, s23, 0
	s_nop 4
	v_cvt_pk_bf16_f32 v8, v8, v9
	v_cvt_pk_bf16_f32 v9, v10, v11
	ds_write_b64 v63, v[8:9] offset:9216
	ds_read_b64 v[10:11], v90 offset:39168
	s_waitcnt lgkmcnt(0)
	v_lshlrev_b32_e32 v8, 16, v10
	v_and_b32_e32 v9, 0xffff0000, v10
	v_lshlrev_b32_e32 v10, 16, v11
	v_and_b32_e32 v11, 0xffff0000, v11
	s_nop 1
	v_mfma_f32_16x16x32_bf16 v[0:3], v[0:3], v[16:19], v[8:11]
	global_store_dwordx4 v204, v[12:15], s[90:91] offset:2048
	v_add_u32_e32 v204, 0xe8000, v204
	ds_read_b128 v[8:11], v67 offset:64
	s_waitcnt lgkmcnt(0)
	v_mfma_f32_16x16x32_bf16 v[0:3], v[4:7], v[8:11], v[0:3]
	s_nop 7
	v_cvt_pk_bf16_f32 v0, v0, v1
	v_cvt_pk_bf16_f32 v1, v2, v3
	ds_write_b64 v64, v[0:1] offset:9216
	s_waitcnt lgkmcnt(0)
	s_barrier
	s_mov_b64 s[10:11], s[92:93]
	ds_read_b128 v[0:3], v60 offset:9216
	ds_read_b128 v[72:75], v66 offset:9216
	v_lshl_add_u32 v84, v50, 2, s34
	s_mul_i32 s22, s29, 0x9100
	s_waitcnt lgkmcnt(0)
	v_lshl_add_u64 v[4:5], s[10:11], 0, v[56:57]
	global_store_dwordx4 v[4:5], v[0:3], off
	global_load_dwordx4 v[16:19], v203, s[94:95]
	s_nop 0
	global_load_dwordx4 v[0:3], v202, s[12:13]
	s_add_i32 s30, s22, 0
	global_load_dwordx4 v[4:7], v202, s[14:15]
	global_load_dwordx4 v[8:11], v202, s[16:17]
	global_load_dwordx4 v[12:15], v202, s[18:19]
	v_add_u32_e32 v202, 0x40000, v202
	v_add_u32_e32 v203, 0x2000, v203
	ds_read_b64 v[88:89], v90 offset:46080
	ds_read_b128 v[76:79], v80 offset:27648
	ds_read_b128 v[80:83], v80 offset:27712
	ds_read_b128 v[84:87], v84 offset:55296
	ds_read_b64 v[92:93], v90 offset:48384
	s_waitcnt lgkmcnt(4)
	v_lshlrev_b32_e32 v90, 16, v88
	v_and_b32_e32 v91, 0xffff0000, v88
	v_lshlrev_b32_e32 v88, 16, v89
	v_and_b32_e32 v89, 0xffff0000, v89
	s_waitcnt lgkmcnt(1)
	v_pk_fma_f32 v[26:27], v[26:27], v[86:87], v[88:89]
	v_pk_fma_f32 v[24:25], v[24:25], v[84:85], v[90:91]
	s_nop 1
	v_mfma_f32_16x16x32_bf16 v[24:27], v[76:79], v[72:75], v[24:27]
	ds_read_b128 v[72:75], v66 offset:9280
	ds_read_b128 v[88:91], v67 offset:9216
	s_waitcnt lgkmcnt(1)
	v_mfma_f32_16x16x32_bf16 v[24:27], v[80:83], v[72:75], v[24:27]
	v_lshlrev_b32_e32 v72, 16, v92
	v_and_b32_e32 v73, 0xffff0000, v92
	v_lshlrev_b32_e32 v74, 16, v93
	v_and_b32_e32 v75, 0xffff0000, v93
	v_pk_fma_f32 v[22:23], v[22:23], v[86:87], v[74:75]
	v_pk_fma_f32 v[20:21], v[20:21], v[84:85], v[72:73]
	ds_read_b128 v[72:75], v67 offset:9280
	s_waitcnt lgkmcnt(1)
	v_mfma_f32_16x16x32_bf16 v[20:23], v[76:79], v[88:91], v[20:23]
	s_waitcnt lgkmcnt(0)
	v_mfma_f32_16x16x32_bf16 v[20:23], v[80:83], v[72:75], v[20:23]
	v_cvt_pk_bf16_f32 v72, v24, v25
	v_cvt_pk_bf16_f32 v73, v26, v27
	ds_write_b64 v63, v[72:73]
	s_nop 4
	v_cvt_pk_bf16_f32 v72, v20, v21
	v_cvt_pk_bf16_f32 v73, v22, v23
	ds_write_b64 v64, v[72:73]
	s_waitcnt lgkmcnt(0)
	s_barrier
	v_add3_u32 v72, s30, v51, v48
	s_waitcnt vmcnt(11)
	ds_write_b128 v72, v[32:35] offset:18432
	s_waitcnt vmcnt(10)
	ds_write_b128 v72, v[36:39] offset:27648
	s_waitcnt vmcnt(8)
	ds_write_b128 v72, v[40:43] offset:36864
	ds_write_b128 v72, v[44:47] offset:46080
	s_and_saveexec_b64 s[22:23], s[8:9]
	s_cbranch_execz .LBB0_437
	v_lshl_add_u32 v32, v134, 2, s30
	s_waitcnt vmcnt(7)
	ds_write_b128 v32, v[28:31] offset:55296
	s_branch .LBB0_437
